# v13 + attention queue: first item of each attention-only workgroup is static (bid-128), later pops are 128+fetch_add: removes the 128-way single-address atomic burst at P2 start
# speedup vs baseline: 1.0122x; 1.0109x over previous
; #define LAS __attribute__((address_space(3)))
; __device__ __forceinline__ int swap23(int r) { return (r & ~12) | ((r & 4) << 1) | ((r & 8) >> 1); }
; __device__ __forceinline__ void phase_attn(const Params& p, LAS unsigned char* lds, unsigned* queue) {
;     const int tid = threadIdx.x, lane = tid & 63, w = __builtin_amdgcn_readfirstlane(tid >> 6), r = lane & 31, hh = lane >> 5;
;     const bf16_t* Qg = (const bf16_t*)(p.ws + WS_Q); const bf16_t* Kg = (const bf16_t*)(p.ws + WS_K); const bf16_t* VTg = (const bf16_t*)(p.ws + WS_VT);
;     const bf16_t* SZA = (const bf16_t*)(p.ws + WS_SZA); const float* KSUM = (const float*)(p.ws + WS_KSUM);
;     bf16_t* MIXED = (bf16_t*)(p.ws + WS_XB);
;     constexpr int ROWB = 144, TILEB = 64 * ROWB, BUFB = 2 * TILEB;
;     const int srow = tid >> 3, sch = tid & 7;
;     const unsigned st_off = (unsigned)(srow * ROWB + sch * 16);
;     const unsigned kf_off = (unsigned)(swap23(r) * ROWB + hh * 16);
;     const unsigned vf_off = (unsigned)(TILEB + r * ROWB + hh * 16);
;     volatile LAS unsigned* tick = (volatile LAS unsigned*)(lds + LDS_CTL + 8);
;     for (;;) {
;         if (tid == 0) *tick = __hip_atomic_fetch_add(queue, 1u, __ATOMIC_RELAXED, __HIP_MEMORY_SCOPE_AGENT);
.LBB0_330:
	v_mov_b32_e32 v251, 1
	s_add_u32 s0, s78, 0xbd03a00
	s_addc_u32 s1, s79, 0
	v_and_b32_e32 v3, 7, v0
	v_lshlrev_b32_e32 v5, 1, v0
	v_writelane_b32 v255, s0, 6
	v_bfe_u32 v8, v0, 5, 1
	v_lshlrev_b32_e32 v4, 4, v3
	v_and_b32_e32 v3, 19, v0
	v_and_b32_e32 v5, 8, v5
	v_and_b32_e32 v2, 4, v2
	v_writelane_b32 v255, s1, 7
	s_movk_i32 s1, 0x90
	v_or3_b32 v3, v3, v5, v2
	v_lshlrev_b32_e32 v2, 4, v8
	v_mad_u32_u24 v197, v3, s1, v2
	v_mov_b32_e32 v3, 0
	v_readfirstlane_b32 s0, v0
	v_lshlrev_b32_e32 v6, 5, v8
	v_mov_b32_e32 v7, v3
	s_lshr_b32 s3, s0, 1
	v_lshl_add_u64 v[180:181], s[10:11], 0, v[6:7]
	v_lshlrev_b32_e32 v6, 12, v200
	s_and_b32 s3, s3, 0x7fffffe0
	v_mov_b32_e32 v5, v3
	v_lshl_add_u64 v[6:7], s[8:9], 0, v[6:7]
	v_mbcnt_hi_u32_b32 v192, -1, v250
	v_mul_u32_u24_e32 v9, 0x90, v200
	v_or_b32_e32 v199, s3, v212
	v_lshl_add_u64 v[178:179], s[12:13], 0, v[2:3]
	v_lshl_add_u64 v[184:185], v[6:7], 0, v[4:5]
	s_lshr_b32 s3, s0, 7
	v_lshlrev_b32_e32 v6, 2, v8
	v_mad_u32_u24 v205, v212, s1, v2
	s_add_i32 s90, 0, 0x22008
	v_and_b32_e32 v2, 64, v192
	v_lshlrev_b32_e32 v203, 3, v8
	v_lshl_add_u64 v[182:183], s[6:7], 0, v[4:5]
	s_mov_b32 s83, 0
	v_add3_u32 v204, v9, v4, 0
	s_lshl_b32 s88, s3, 6
	s_add_i32 s89, s3, -1
	v_mov_b32_e32 v212, s90
	s_mov_b32 s91, 0x41000000
	v_lshlrev_b32_e32 v186, 1, v6
	v_xor_b32_e32 v193, 32, v192
	v_add_u32_e32 v202, 64, v2
	v_mov_b32_e32 v211, 0xf149f2ca
	s_branch .LBB0_333

; __device__ __forceinline__ void phase_attn(const Params& p, LAS unsigned char* lds, unsigned* queue) {
;     ...
;         if (tid == 0) *tick = __hip_atomic_fetch_add(queue, 1u, __ATOMIC_RELAXED, __HIP_MEMORY_SCOPE_AGENT);
;         __syncthreads();
;         const int idx = (int)*tick;
;         if (idx >= 512) break;
.LBB0_333:
	s_and_saveexec_b64 s[4:5], s[92:93]
	s_cbranch_execz .LBB0_337
	s_mov_b64 s[8:9], exec
	v_mbcnt_lo_u32_b32 v2, s8, 0
	v_mbcnt_hi_u32_b32 v2, s9, v2
	v_cmp_eq_u32_e32 vcc, 0, v2
	s_and_saveexec_b64 s[6:7], vcc
	s_cbranch_execz .LBB0_336
	v_readfirstlane_b32 s98, v251
	v_mov_b32_e32 v251, 0
	s_cmp_eq_u32 s98, 1
	s_cselect_b32 s98, 1, 0
	s_cmpk_gt_i32 s2, 0x7f
	s_cselect_b32 s99, 1, 0
	s_and_b32 s98, s98, s99
	s_cmp_eq_u32 s98, 1
	s_cbranch_scc0 .Lq_dyn
	s_sub_i32 s0, s2, 0x80
	v_mov_b32_e32 v4, s0
	s_branch .LBB0_336
.Lq_dyn:
	s_bcnt1_i32_b64 s0, s[8:9]
	v_mov_b32_e32 v4, s0
	v_readlane_b32 s0, v255, 6
	v_readlane_b32 s1, v255, 7
	s_nop 4
	global_atomic_add v4, v3, v4, s[0:1] sc0
	s_waitcnt vmcnt(0)
	v_add_u32_e32 v4, 0x80, v4
